# phase A2 prompt-row RMS norm body rewritten by hand: whole row and modulation vectors requested in batches (was one or two loads per wait)
# speedup vs baseline: 1.0082x; 1.0082x over previous
.LBB0_256:
	v_lshl_add_u64 v[76:77], s[40:41], 0, v[2:3]
	global_load_dwordx4 v[4:7], v[76:77], off
	global_load_dwordx4 v[8:11], v[76:77], off offset:1024
	global_load_dwordx4 v[12:15], v[76:77], off offset:2048
	global_load_dwordx4 v[16:19], v[76:77], off offset:3072
	s_mov_b64 s[42:43], 0x1000
	v_lshl_add_u64 v[78:79], v[76:77], 0, s[42:43]
	global_load_dwordx4 v[20:23], v[78:79], off
	global_load_dwordx4 v[24:27], v[78:79], off offset:1024
	global_load_dwordx4 v[28:31], v[78:79], off offset:2048
	global_load_dwordx4 v[32:35], v[78:79], off offset:3072
	s_mov_b64 s[42:43], 0x2000
	v_lshl_add_u64 v[80:81], v[76:77], 0, s[42:43]
	global_load_dwordx4 v[36:39], v[80:81], off
	global_load_dwordx4 v[40:43], v[80:81], off offset:1024
	global_load_dwordx4 v[44:47], v[80:81], off offset:2048
	global_load_dwordx4 v[48:51], v[80:81], off offset:3072
	s_mov_b64 s[42:43], 0x3000
	v_lshl_add_u64 v[74:75], v[76:77], 0, s[42:43]
	global_load_dwordx4 v[52:55], v[74:75], off
	global_load_dwordx4 v[56:59], v[74:75], off offset:1024
	global_load_dwordx4 v[60:63], v[74:75], off offset:2048
	global_load_dwordx4 v[64:67], v[74:75], off offset:3072
	s_lshr_b32 s10, s10, 5
	s_add_i32 s10, s10, 4
	s_ashr_i32 s40, s2, 12
	s_and_b64 s[38:39], s[38:39], exec
	s_cselect_b32 s10, s40, s10
	s_mul_i32 s38, s10, 3
	s_ashr_i32 s39, s38, 31
	s_lshl_b64 s[38:39], s[38:39], 14
	s_lshl_b64 s[36:37], s[36:37], 13
	v_lshl_add_u64 v[112:113], v[68:69], 0, s[38:39]
	s_mov_b64 s[42:43], 0x4000
	v_lshl_add_u64 v[110:111], v[112:113], 0, s[42:43]
	v_lshl_add_u64 v[108:109], v[70:71], 0, s[36:37]
	s_mov_b64 s[42:43], 0x1000
	v_lshl_add_u64 v[106:107], v[108:109], 0, s[42:43]
	global_load_dwordx4 v[116:119], v[112:113], off
	global_load_dwordx4 v[120:123], v[112:113], off offset:1024
	global_load_dwordx4 v[124:127], v[112:113], off offset:2048
	global_load_dwordx4 v[128:131], v[112:113], off offset:3072
	global_load_dwordx4 v[132:135], v[110:111], off
	global_load_dwordx4 v[136:139], v[110:111], off offset:1024
	global_load_dwordx4 v[140:143], v[110:111], off offset:2048
	global_load_dwordx4 v[144:147], v[110:111], off offset:3072
	s_add_u32 s2, s2, s4
	s_addc_u32 s3, s3, s5
	s_add_u32 s6, s6, s8
	s_addc_u32 s7, s7, s9
	s_waitcnt vmcnt(8)
	v_pk_mul_f32 v[88:89], v[4:5], v[4:5]
	v_pk_fma_f32 v[88:89], v[6:7], v[6:7], v[88:89]
	v_pk_mul_f32 v[90:91], v[8:9], v[8:9]
	v_pk_fma_f32 v[90:91], v[10:11], v[10:11], v[90:91]
	v_pk_add_f32 v[88:89], v[88:89], v[90:91]
	v_pk_mul_f32 v[90:91], v[12:13], v[12:13]
	v_pk_fma_f32 v[90:91], v[14:15], v[14:15], v[90:91]
	v_pk_add_f32 v[88:89], v[88:89], v[90:91]
	v_pk_mul_f32 v[90:91], v[16:17], v[16:17]
	v_pk_fma_f32 v[90:91], v[18:19], v[18:19], v[90:91]
	v_pk_add_f32 v[88:89], v[88:89], v[90:91]
	v_pk_mul_f32 v[90:91], v[20:21], v[20:21]
	v_pk_fma_f32 v[90:91], v[22:23], v[22:23], v[90:91]
	v_pk_add_f32 v[88:89], v[88:89], v[90:91]
	v_pk_mul_f32 v[90:91], v[24:25], v[24:25]
	v_pk_fma_f32 v[90:91], v[26:27], v[26:27], v[90:91]
	v_pk_add_f32 v[88:89], v[88:89], v[90:91]
	v_pk_mul_f32 v[90:91], v[28:29], v[28:29]
	v_pk_fma_f32 v[90:91], v[30:31], v[30:31], v[90:91]
	v_pk_add_f32 v[88:89], v[88:89], v[90:91]
	v_pk_mul_f32 v[90:91], v[32:33], v[32:33]
	v_pk_fma_f32 v[90:91], v[34:35], v[34:35], v[90:91]
	v_pk_add_f32 v[88:89], v[88:89], v[90:91]
	v_pk_mul_f32 v[90:91], v[36:37], v[36:37]
	v_pk_fma_f32 v[90:91], v[38:39], v[38:39], v[90:91]
	v_pk_add_f32 v[88:89], v[88:89], v[90:91]
	v_pk_mul_f32 v[90:91], v[40:41], v[40:41]
	v_pk_fma_f32 v[90:91], v[42:43], v[42:43], v[90:91]
	v_pk_add_f32 v[88:89], v[88:89], v[90:91]
	v_pk_mul_f32 v[90:91], v[44:45], v[44:45]
	v_pk_fma_f32 v[90:91], v[46:47], v[46:47], v[90:91]
	v_pk_add_f32 v[88:89], v[88:89], v[90:91]
	v_pk_mul_f32 v[90:91], v[48:49], v[48:49]
	v_pk_fma_f32 v[90:91], v[50:51], v[50:51], v[90:91]
	v_pk_add_f32 v[88:89], v[88:89], v[90:91]
	v_pk_mul_f32 v[90:91], v[52:53], v[52:53]
	v_pk_fma_f32 v[90:91], v[54:55], v[54:55], v[90:91]
	v_pk_add_f32 v[88:89], v[88:89], v[90:91]
	v_pk_mul_f32 v[90:91], v[56:57], v[56:57]
	v_pk_fma_f32 v[90:91], v[58:59], v[58:59], v[90:91]
	v_pk_add_f32 v[88:89], v[88:89], v[90:91]
	v_pk_mul_f32 v[90:91], v[60:61], v[60:61]
	v_pk_fma_f32 v[90:91], v[62:63], v[62:63], v[90:91]
	v_pk_add_f32 v[88:89], v[88:89], v[90:91]
	v_pk_mul_f32 v[90:91], v[64:65], v[64:65]
	v_pk_fma_f32 v[90:91], v[66:67], v[66:67], v[90:91]
	v_pk_add_f32 v[88:89], v[88:89], v[90:91]
	s_nop 0
	v_add_f32_e32 v72, v88, v89
	ds_bpermute_b32 v74, v73, v72
	s_waitcnt lgkmcnt(0)
	v_add_f32_e32 v72, v72, v74
	ds_bpermute_b32 v74, v82, v72
	s_waitcnt lgkmcnt(0)
	v_add_f32_e32 v72, v72, v74
	ds_bpermute_b32 v74, v83, v72
	s_waitcnt lgkmcnt(0)
	v_add_f32_e32 v72, v72, v74
	ds_bpermute_b32 v74, v84, v72
	s_waitcnt lgkmcnt(0)
	v_add_f32_e32 v72, v72, v74
	ds_bpermute_b32 v74, v85, v72
	s_waitcnt lgkmcnt(0)
	v_add_f32_e32 v72, v72, v74
	ds_bpermute_b32 v74, v86, v72
	s_waitcnt lgkmcnt(0)
	v_add_f32_e32 v72, v72, v74
	v_fmamk_f32 v72, v72, 0x39800000, v1
	v_cmp_gt_f32_e32 vcc, s33, v72
	v_mul_f32_e32 v74, 0x4b800000, v72
	s_nop 0
	v_cndmask_b32_e32 v72, v72, v74, vcc
	v_rsq_f32_e32 v72, v72
	s_nop 0
	v_mul_f32_e32 v74, 0x45800000, v72
	v_cndmask_b32_e32 v72, v72, v74, vcc
	s_mov_b64 s[42:43], 0x1000
	v_lshl_add_u64 v[114:115], v[112:113], 0, s[42:43]
	v_lshl_add_u64 v[104:105], v[110:111], 0, s[42:43]
	global_load_dwordx4 v[206:209], v[114:115], off
	global_load_dwordx4 v[210:213], v[114:115], off offset:1024
	global_load_dwordx4 v[214:217], v[114:115], off offset:2048
	global_load_dwordx4 v[218:221], v[114:115], off offset:3072
	global_load_dwordx4 v[222:225], v[104:105], off
	global_load_dwordx4 v[226:229], v[104:105], off offset:1024
	global_load_dwordx4 v[230:233], v[104:105], off offset:2048
	global_load_dwordx4 v[234:237], v[104:105], off offset:3072
	s_waitcnt vmcnt(8)
	v_pk_mul_f32 v[4:5], v[72:73], v[4:5] op_sel_hi:[0,1]
	v_pk_mul_f32 v[6:7], v[72:73], v[6:7] op_sel_hi:[0,1]
	v_pk_fma_f32 v[4:5], v[116:117], v[4:5], v[132:133]
	v_pk_fma_f32 v[6:7], v[118:119], v[6:7], v[134:135]
	v_cvt_pk_bf16_f32 v4, v4, v5
	v_cvt_pk_bf16_f32 v5, v6, v7
	global_store_dwordx2 v[108:109], v[4:5], off
	v_pk_mul_f32 v[8:9], v[72:73], v[8:9] op_sel_hi:[0,1]
	v_pk_mul_f32 v[10:11], v[72:73], v[10:11] op_sel_hi:[0,1]
	v_pk_fma_f32 v[8:9], v[120:121], v[8:9], v[136:137]
	v_pk_fma_f32 v[10:11], v[122:123], v[10:11], v[138:139]
	v_cvt_pk_bf16_f32 v8, v8, v9
	v_cvt_pk_bf16_f32 v9, v10, v11
	global_store_dwordx2 v[108:109], v[8:9], off offset:512
	v_pk_mul_f32 v[12:13], v[72:73], v[12:13] op_sel_hi:[0,1]
	v_pk_mul_f32 v[14:15], v[72:73], v[14:15] op_sel_hi:[0,1]
	v_pk_fma_f32 v[12:13], v[124:125], v[12:13], v[140:141]
	v_pk_fma_f32 v[14:15], v[126:127], v[14:15], v[142:143]
	v_cvt_pk_bf16_f32 v12, v12, v13
	v_cvt_pk_bf16_f32 v13, v14, v15
	global_store_dwordx2 v[108:109], v[12:13], off offset:1024
	v_pk_mul_f32 v[16:17], v[72:73], v[16:17] op_sel_hi:[0,1]
	v_pk_mul_f32 v[18:19], v[72:73], v[18:19] op_sel_hi:[0,1]
	v_pk_fma_f32 v[16:17], v[128:129], v[16:17], v[144:145]
	v_pk_fma_f32 v[18:19], v[130:131], v[18:19], v[146:147]
	v_cvt_pk_bf16_f32 v16, v16, v17
	v_cvt_pk_bf16_f32 v17, v18, v19
	global_store_dwordx2 v[108:109], v[16:17], off offset:1536
	s_mov_b64 s[42:43], 0x2000
	v_lshl_add_u64 v[114:115], v[112:113], 0, s[42:43]
	v_lshl_add_u64 v[104:105], v[110:111], 0, s[42:43]
	global_load_dwordx4 v[116:119], v[114:115], off
	global_load_dwordx4 v[120:123], v[114:115], off offset:1024
	global_load_dwordx4 v[124:127], v[114:115], off offset:2048
	global_load_dwordx4 v[128:131], v[114:115], off offset:3072
	global_load_dwordx4 v[132:135], v[104:105], off
	global_load_dwordx4 v[136:139], v[104:105], off offset:1024
	global_load_dwordx4 v[140:143], v[104:105], off offset:2048
	global_load_dwordx4 v[144:147], v[104:105], off offset:3072
	s_waitcnt vmcnt(12)
	v_pk_mul_f32 v[20:21], v[72:73], v[20:21] op_sel_hi:[0,1]
	v_pk_mul_f32 v[22:23], v[72:73], v[22:23] op_sel_hi:[0,1]
	v_pk_fma_f32 v[20:21], v[206:207], v[20:21], v[222:223]
	v_pk_fma_f32 v[22:23], v[208:209], v[22:23], v[224:225]
	v_cvt_pk_bf16_f32 v20, v20, v21
	v_cvt_pk_bf16_f32 v21, v22, v23
	global_store_dwordx2 v[108:109], v[20:21], off offset:2048
	v_pk_mul_f32 v[24:25], v[72:73], v[24:25] op_sel_hi:[0,1]
	v_pk_mul_f32 v[26:27], v[72:73], v[26:27] op_sel_hi:[0,1]
	v_pk_fma_f32 v[24:25], v[210:211], v[24:25], v[226:227]
	v_pk_fma_f32 v[26:27], v[212:213], v[26:27], v[228:229]
	v_cvt_pk_bf16_f32 v24, v24, v25
	v_cvt_pk_bf16_f32 v25, v26, v27
	global_store_dwordx2 v[108:109], v[24:25], off offset:2560
	v_pk_mul_f32 v[28:29], v[72:73], v[28:29] op_sel_hi:[0,1]
	v_pk_mul_f32 v[30:31], v[72:73], v[30:31] op_sel_hi:[0,1]
	v_pk_fma_f32 v[28:29], v[214:215], v[28:29], v[230:231]
	v_pk_fma_f32 v[30:31], v[216:217], v[30:31], v[232:233]
	v_cvt_pk_bf16_f32 v28, v28, v29
	v_cvt_pk_bf16_f32 v29, v30, v31
	global_store_dwordx2 v[108:109], v[28:29], off offset:3072
	v_pk_mul_f32 v[32:33], v[72:73], v[32:33] op_sel_hi:[0,1]
	v_pk_mul_f32 v[34:35], v[72:73], v[34:35] op_sel_hi:[0,1]
	v_pk_fma_f32 v[32:33], v[218:219], v[32:33], v[234:235]
	v_pk_fma_f32 v[34:35], v[220:221], v[34:35], v[236:237]
	v_cvt_pk_bf16_f32 v32, v32, v33
	v_cvt_pk_bf16_f32 v33, v34, v35
	global_store_dwordx2 v[108:109], v[32:33], off offset:3584
	s_mov_b64 s[42:43], 0x3000
	v_lshl_add_u64 v[114:115], v[112:113], 0, s[42:43]
	v_lshl_add_u64 v[104:105], v[110:111], 0, s[42:43]
	global_load_dwordx4 v[206:209], v[114:115], off
	global_load_dwordx4 v[210:213], v[114:115], off offset:1024
	global_load_dwordx4 v[214:217], v[114:115], off offset:2048
	global_load_dwordx4 v[218:221], v[114:115], off offset:3072
	global_load_dwordx4 v[222:225], v[104:105], off
	global_load_dwordx4 v[226:229], v[104:105], off offset:1024
	global_load_dwordx4 v[230:233], v[104:105], off offset:2048
	global_load_dwordx4 v[234:237], v[104:105], off offset:3072
	s_waitcnt vmcnt(12)
	v_pk_mul_f32 v[36:37], v[72:73], v[36:37] op_sel_hi:[0,1]
	v_pk_mul_f32 v[38:39], v[72:73], v[38:39] op_sel_hi:[0,1]
	v_pk_fma_f32 v[36:37], v[116:117], v[36:37], v[132:133]
	v_pk_fma_f32 v[38:39], v[118:119], v[38:39], v[134:135]
	v_cvt_pk_bf16_f32 v36, v36, v37
	v_cvt_pk_bf16_f32 v37, v38, v39
	global_store_dwordx2 v[106:107], v[36:37], off
	v_pk_mul_f32 v[40:41], v[72:73], v[40:41] op_sel_hi:[0,1]
	v_pk_mul_f32 v[42:43], v[72:73], v[42:43] op_sel_hi:[0,1]
	v_pk_fma_f32 v[40:41], v[120:121], v[40:41], v[136:137]
	v_pk_fma_f32 v[42:43], v[122:123], v[42:43], v[138:139]
	v_cvt_pk_bf16_f32 v40, v40, v41
	v_cvt_pk_bf16_f32 v41, v42, v43
	global_store_dwordx2 v[106:107], v[40:41], off offset:512
	v_pk_mul_f32 v[44:45], v[72:73], v[44:45] op_sel_hi:[0,1]
	v_pk_mul_f32 v[46:47], v[72:73], v[46:47] op_sel_hi:[0,1]
	v_pk_fma_f32 v[44:45], v[124:125], v[44:45], v[140:141]
	v_pk_fma_f32 v[46:47], v[126:127], v[46:47], v[142:143]
	v_cvt_pk_bf16_f32 v44, v44, v45
	v_cvt_pk_bf16_f32 v45, v46, v47
	global_store_dwordx2 v[106:107], v[44:45], off offset:1024
	v_pk_mul_f32 v[48:49], v[72:73], v[48:49] op_sel_hi:[0,1]
	v_pk_mul_f32 v[50:51], v[72:73], v[50:51] op_sel_hi:[0,1]
	v_pk_fma_f32 v[48:49], v[128:129], v[48:49], v[144:145]
	v_pk_fma_f32 v[50:51], v[130:131], v[50:51], v[146:147]
	v_cvt_pk_bf16_f32 v48, v48, v49
	v_cvt_pk_bf16_f32 v49, v50, v51
	global_store_dwordx2 v[106:107], v[48:49], off offset:1536
	s_waitcnt vmcnt(4)
	v_pk_mul_f32 v[52:53], v[72:73], v[52:53] op_sel_hi:[0,1]
	v_pk_mul_f32 v[54:55], v[72:73], v[54:55] op_sel_hi:[0,1]
	v_pk_fma_f32 v[52:53], v[206:207], v[52:53], v[222:223]
	v_pk_fma_f32 v[54:55], v[208:209], v[54:55], v[224:225]
	v_cvt_pk_bf16_f32 v52, v52, v53
	v_cvt_pk_bf16_f32 v53, v54, v55
	global_store_dwordx2 v[106:107], v[52:53], off offset:2048
	v_pk_mul_f32 v[56:57], v[72:73], v[56:57] op_sel_hi:[0,1]
	v_pk_mul_f32 v[58:59], v[72:73], v[58:59] op_sel_hi:[0,1]
	v_pk_fma_f32 v[56:57], v[210:211], v[56:57], v[226:227]
	v_pk_fma_f32 v[58:59], v[212:213], v[58:59], v[228:229]
	v_cvt_pk_bf16_f32 v56, v56, v57
	v_cvt_pk_bf16_f32 v57, v58, v59
	global_store_dwordx2 v[106:107], v[56:57], off offset:2560
	v_pk_mul_f32 v[60:61], v[72:73], v[60:61] op_sel_hi:[0,1]
	v_pk_mul_f32 v[62:63], v[72:73], v[62:63] op_sel_hi:[0,1]
	v_pk_fma_f32 v[60:61], v[214:215], v[60:61], v[230:231]
	v_pk_fma_f32 v[62:63], v[216:217], v[62:63], v[232:233]
	v_cvt_pk_bf16_f32 v60, v60, v61
	v_cvt_pk_bf16_f32 v61, v62, v63
	global_store_dwordx2 v[106:107], v[60:61], off offset:3072
	v_pk_mul_f32 v[64:65], v[72:73], v[64:65] op_sel_hi:[0,1]
	v_pk_mul_f32 v[66:67], v[72:73], v[66:67] op_sel_hi:[0,1]
	v_pk_fma_f32 v[64:65], v[218:219], v[64:65], v[234:235]
	v_pk_fma_f32 v[66:67], v[220:221], v[66:67], v[236:237]
	v_cvt_pk_bf16_f32 v64, v64, v65
	v_cvt_pk_bf16_f32 v65, v66, v67
	global_store_dwordx2 v[106:107], v[64:65], off offset:3584
	s_cmp_lt_i32 s2, s47
	s_cbranch_scc0 .LBB0_261
